# v22 + attention unit prologue: forget-gate reference loads issued with the Q/tile-total loads (one round trip less per unit)
# speedup vs baseline: 1.0075x; 1.0075x over previous
; #define LAS __attribute__((address_space(3)))
; __device__ __forceinline__ void fx_attn_unit(const Args& A, Frame& F, int bh, int qb, float qkmax) {
;     ...
; #pragma unroll
;     for (int ks = 0; ks < 4; ++ks) *(LAS u32x4*)(Qw + ks * 1024) = *(const u32x4*)(Qg + (size_t)tq * 4096 + 16 * ks + 8 * hh);
;     float Gw;
;     float l = 0.f; f32x16 o0, o1;
; #pragma unroll
;     for (int e = 0; e < 16; ++e) { o0[e] = 0.f; o1[e] = 0.f; }
;     const int NT = 4 * qb + 4;
;     const int ss_ = tid >> 3, ch = tid & 7;
;     int jstart; float gbase;
;     { const float f0 = lane < NT ? FTp[lane] : 0.f, f1 = 64 + lane < NT ? FTp[64 + lane] : 0.f;
;       const float s0 = wave_scan_incl(f0, lane); const float s1 = __shfl(s0, 63) + wave_scan_incl(f1, lane);
;       const int jt0 = 4 * qb;
;       const float pre0 = jt0 == 0 ? 0.f : (jt0 - 1 < 64 ? __shfl(s0, jt0 - 1) : __shfl(s1, jt0 - 1 - 64));
;       const float Gw0 = pre0 + FLp[q0 + 16];
;       { const int tref = q0 + 32 * wave + 16, jt = tref >> 6;
;         const float prew = jt == 0 ? 0.f : (jt - 1 < 64 ? __shfl(s0, jt - 1) : __shfl(s1, jt - 1 - 64)); Gw = prew + FLp[tref]; }
;       const unsigned long long z0 = __ballot(lane < NT && (qkmax + s0 - Gw0 < -152.0f)), z1 = __ballot(64 + lane < NT && (qkmax + s1 - Gw0 < -152.0f));
.LBB0_683:
	s_or_b64 exec, exec, s[28:29]
	v_readlane_b32 s28, v253, 31
	v_readlane_b32 s29, v253, 32
	v_mov_b32_e32 v28, s35
	v_lshlrev_b32_e32 v28, 15, v28
	v_lshl_add_u32 v28, s34, 2, v28
	v_lshl_add_u32 v30, s4, 2, v28
	s_nop 1
	global_load_dword v29, v28, s[28:29] offset:64
	global_load_dword v31, v30, s[28:29] offset:64
	s_waitcnt vmcnt(0)
	ds_write_b128 v214, v[12:15]
	ds_write_b128 v214, v[16:19] offset:1024
	ds_write_b128 v214, v[20:23] offset:2048
	ds_write_b128 v214, v[24:27] offset:3072
	ds_bpermute_b32 v0, v180, v3
	ds_bpermute_b32 v4, v180, v2
	s_cmp_eq_u32 s47, 31
	v_mov_b32_e32 v5, 0
	s_waitcnt lgkmcnt(1)
	v_add_f32_e32 v0, v3, v0
	v_cndmask_b32_e64 v0, v0, v3, s[8:9]
	ds_bpermute_b32 v3, v181, v0
	s_waitcnt lgkmcnt(1)
	v_add_f32_e32 v4, v2, v4
	v_cndmask_b32_e64 v2, v4, v2, s[8:9]
	ds_bpermute_b32 v4, v181, v2
	s_waitcnt lgkmcnt(1)
	v_add_f32_e32 v3, v0, v3
	v_cndmask_b32_e64 v0, v3, v0, s[10:11]
	ds_bpermute_b32 v3, v200, v0
	s_waitcnt lgkmcnt(1)
	v_add_f32_e32 v4, v2, v4
	v_cndmask_b32_e64 v2, v4, v2, s[10:11]
	ds_bpermute_b32 v4, v200, v2
	s_waitcnt lgkmcnt(1)
	v_add_f32_e32 v3, v0, v3
	v_cndmask_b32_e64 v0, v3, v0, s[12:13]
	ds_bpermute_b32 v3, v201, v0
	s_waitcnt lgkmcnt(1)
	v_add_f32_e32 v4, v2, v4
	v_cndmask_b32_e64 v2, v4, v2, s[12:13]
	ds_bpermute_b32 v4, v201, v2
	s_waitcnt lgkmcnt(1)
	v_add_f32_e32 v3, v0, v3
	v_cndmask_b32_e64 v0, v3, v0, s[14:15]
	ds_bpermute_b32 v3, v202, v0
	s_waitcnt lgkmcnt(1)
	v_add_f32_e32 v4, v2, v4
	v_cndmask_b32_e64 v2, v4, v2, s[14:15]
	ds_bpermute_b32 v4, v202, v2
	s_waitcnt lgkmcnt(1)
	v_add_f32_e32 v3, v0, v3
	v_cndmask_b32_e64 v0, v3, v0, s[16:17]
	ds_bpermute_b32 v3, v203, v0
	s_waitcnt lgkmcnt(1)
	v_add_f32_e32 v4, v2, v4
	v_cndmask_b32_e64 v2, v4, v2, s[16:17]
	ds_bpermute_b32 v4, v203, v2
	s_waitcnt lgkmcnt(1)
	v_add_f32_e32 v3, v0, v3
	v_cndmask_b32_e64 v0, v3, v0, s[18:19]
	ds_bpermute_b32 v3, v204, v0
	s_waitcnt lgkmcnt(1)
	v_add_f32_e32 v4, v2, v4
	v_cndmask_b32_e64 v2, v4, v2, s[18:19]
	s_waitcnt lgkmcnt(0)
	v_add_f32_e32 v3, v2, v3
	v_mov_b32_e32 v2, 0
	s_cbranch_scc1 .LBB0_688
	s_add_i32 s47, s45, 63
	s_cmpk_lt_u32 s46, 0x3c0
	s_mov_b64 s[28:29], -1
	v_and_or_b32 v4, s47, 63, v194
	s_cbranch_scc0 .LBB0_686
	v_lshlrev_b32_e32 v5, 2, v4
	ds_bpermute_b32 v5, v5, v3
	s_mov_b64 s[28:29], 0

; __device__ __forceinline__ void fx_attn_unit(const Args& A, Frame& F, int bh, int qb, float qkmax) {
;     ...
;       const float s0 = wave_scan_incl(f0, lane); const float s1 = __shfl(s0, 63) + wave_scan_incl(f1, lane);
;       const int jt0 = 4 * qb;
;       const float pre0 = jt0 == 0 ? 0.f : (jt0 - 1 < 64 ? __shfl(s0, jt0 - 1) : __shfl(s1, jt0 - 1 - 64));
;       const float Gw0 = pre0 + FLp[q0 + 16];
;       { const int tref = q0 + 32 * wave + 16, jt = tref >> 6;
;         const float prew = jt == 0 ? 0.f : (jt - 1 < 64 ? __shfl(s0, jt - 1) : __shfl(s1, jt - 1 - 64)); Gw = prew + FLp[tref]; }
.LBB0_688:
	s_lshl_b32 s28, s35, 15
	v_readlane_b32 s46, v253, 31
	v_readlane_b32 s47, v253, 32
	s_add_u32 s28, s46, s28
	s_addc_u32 s29, s47, 0
	s_lshl_b32 s34, s34, 2
	v_mov_b32_e32 v4, s34
	v_mov_b32_e32 v6, v29
	s_add_u32 s46, s28, s34
	s_addc_u32 s47, s29, 0
	s_cmp_lt_u32 s33, 64
	s_cbranch_scc1 .LBB0_693
	s_ashr_i32 s34, s33, 6
	s_add_i32 s48, s34, 63
	s_cmp_gt_i32 s34, 64
	s_mov_b64 s[34:35], -1
	v_and_or_b32 v4, s48, 63, v194
	s_cbranch_scc0 .LBB0_691
	v_lshlrev_b32_e32 v2, 2, v4
	ds_bpermute_b32 v2, v2, v3
	s_mov_b64 s[34:35], 0

; __device__ __forceinline__ void fx_attn_unit(const Args& A, Frame& F, int bh, int qb, float qkmax) {
;     ...
;       const float Gw0 = pre0 + FLp[q0 + 16];
;       { const int tref = q0 + 32 * wave + 16, jt = tref >> 6;
;         const float prew = jt == 0 ? 0.f : (jt - 1 < 64 ? __shfl(s0, jt - 1) : __shfl(s1, jt - 1 - 64)); Gw = prew + FLp[tref]; }
;       const unsigned long long z0 = __ballot(lane < NT && (qkmax + s0 - Gw0 < -152.0f)), z1 = __ballot(64 + lane < NT && (qkmax + s1 - Gw0 < -152.0f));
;       int cnt = __popcll(z0) + __popcll(z1); if (cnt > 4 * qb) cnt = 4 * qb;
;       jstart = cnt & ~1;
;       gbase = jstart == 0 ? 0.f : (jstart - 1 < 64 ? __shfl(s0, jstart - 1) : __shfl(s1, jstart - 1 - 64)); }
.LBB0_693:
	s_lshl_b64 s[34:35], s[4:5], 2
	s_add_u32 s34, s46, s34
	s_addc_u32 s35, s47, s35
	v_mov_b32_e32 v4, v31
	s_waitcnt vmcnt(1) lgkmcnt(0)
	v_add_f32_e32 v5, v5, v6
	v_add_f32_e32 v6, v113, v0
	v_sub_f32_e32 v6, v6, v5
	s_mov_b32 s34, 0xc3180000
	v_cmp_gt_f32_e32 vcc, s34, v6
	s_and_b64 s[0:1], s[0:1], vcc
	v_cndmask_b32_e64 v6, 0, 1, s[0:1]
	v_cmp_ne_u32_e32 vcc, 0, v6
	v_add_f32_e32 v6, v113, v3
	v_sub_f32_e32 v5, v6, v5
	v_cmp_gt_f32_e64 s[0:1], s34, v5
	s_and_b64 s[0:1], s[20:21], s[0:1]
	s_bcnt1_i32_b64 s20, vcc
	v_cndmask_b32_e64 v5, 0, 1, s[0:1]
	v_cmp_ne_u32_e64 s[0:1], 0, v5
	s_bcnt1_i32_b64 s0, s[0:1]
	s_add_i32 s0, s0, s20
	s_min_u32 s20, s0, s45
	s_and_b32 s21, s20, 0x7e
	s_cmp_eq_u32 s21, 0
	s_cbranch_scc1 .LBB0_698
	s_add_i32 s34, s21, 63
	s_cmp_gt_u32 s21, 64
	s_mov_b64 s[0:1], -1
	v_and_or_b32 v6, s34, 63, v194
	s_cbranch_scc0 .LBB0_696
	v_lshlrev_b32_e32 v5, 2, v6
	ds_bpermute_b32 v5, v5, v3
	s_mov_b64 s[0:1], 0
